# fp8 GEMM main loops (P2 gate GEMM, merge and out-projection GEMMs): the s_nop 1 pad in front of each of the 192 v_mfma_scale deleted (operands come from waited LDS reads, no VALU producer within 2 sta
# speedup vs baseline: 1.0038x; 1.0038x over previous
.LBB0_349:
	ds_read_b128 v[16:19], v186
	ds_read_b128 v[20:23], v186 offset:1024
	ds_read_b128 v[24:27], v186 offset:2048
	ds_read_b128 v[28:31], v186 offset:3072
	ds_read_b128 v[0:3], v187
	ds_read_b128 v[4:7], v187 offset:1024
	ds_read_b128 v[8:11], v187 offset:2048
	ds_read_b128 v[12:15], v187 offset:3072
	s_add_u32 s24, s62, 0xfffc0080
	s_addc_u32 s25, s63, -1
	s_cmp_eq_u32 s71, 12
	s_cselect_b32 s69, s1, s25
	s_cselect_b32 s68, s8, s24
	s_cselect_b32 s67, s23, s70
	s_cselect_b32 s66, s39, s65
	v_lshl_add_u64 v[214:215], s[62:63], 0, v[170:171]
	s_add_i32 m0, s81, 0xc000
	ds_read_b128 v[174:177], v188
	ds_read_b128 v[178:181], v188 offset:1024
	ds_read_b128 v[190:193], v188 offset:2048
	ds_read_b128 v[194:197], v188 offset:3072
	ds_read_b128 v[198:201], v188 offset:4096
	ds_read_b128 v[202:205], v188 offset:5120
	ds_read_b128 v[206:209], v188 offset:6144
	ds_read_b128 v[210:213], v188 offset:7168
	global_load_lds_dwordx4 v[214:215], off
	v_lshl_add_u64 v[214:215], s[62:63], 0, v[172:173]
	s_add_i32 m0, s81, 0xe000
	s_nop 0
	global_load_lds_dwordx4 v[214:215], off
	s_waitcnt vmcnt(8)
	s_waitcnt lgkmcnt(0)
	s_barrier
	s_setprio 1
	s_waitcnt lgkmcnt(0)
	v_mfma_scale_f32_16x16x128_f8f6f4 v[156:159], v[16:23], v[174:181], v[156:159], v189, v189 op_sel_hi:[0,0,0]
	v_mfma_scale_f32_16x16x128_f8f6f4 v[152:155], v[24:31], v[174:181], v[152:155], v189, v189 op_sel_hi:[0,0,0]
	v_mfma_scale_f32_16x16x128_f8f6f4 v[148:151], v[16:23], v[190:197], v[148:151], v189, v189 op_sel_hi:[0,0,0]
	v_mfma_scale_f32_16x16x128_f8f6f4 v[144:147], v[24:31], v[190:197], v[144:147], v189, v189 op_sel_hi:[0,0,0]
	v_mfma_scale_f32_16x16x128_f8f6f4 v[140:143], v[16:23], v[198:205], v[140:143], v189, v189 op_sel_hi:[0,0,0]
	v_mfma_scale_f32_16x16x128_f8f6f4 v[136:139], v[24:31], v[198:205], v[136:139], v189, v189 op_sel_hi:[0,0,0]
	v_mfma_scale_f32_16x16x128_f8f6f4 v[132:135], v[16:23], v[206:213], v[132:135], v189, v189 op_sel_hi:[0,0,0]
	v_mfma_scale_f32_16x16x128_f8f6f4 v[128:131], v[24:31], v[206:213], v[128:131], v189, v189 op_sel_hi:[0,0,0]
	s_setprio 0
	s_setprio 1
	v_mfma_scale_f32_16x16x128_f8f6f4 v[92:95], v[0:7], v[174:181], v[92:95], v189, v189 op_sel_hi:[0,0,0]
	v_mfma_scale_f32_16x16x128_f8f6f4 v[88:91], v[8:15], v[174:181], v[88:91], v189, v189 op_sel_hi:[0,0,0]
	v_mfma_scale_f32_16x16x128_f8f6f4 v[84:87], v[0:7], v[190:197], v[84:87], v189, v189 op_sel_hi:[0,0,0]
	v_mfma_scale_f32_16x16x128_f8f6f4 v[80:83], v[8:15], v[190:197], v[80:83], v189, v189 op_sel_hi:[0,0,0]
	v_mfma_scale_f32_16x16x128_f8f6f4 v[76:79], v[0:7], v[198:205], v[76:79], v189, v189 op_sel_hi:[0,0,0]
	v_mfma_scale_f32_16x16x128_f8f6f4 v[72:75], v[8:15], v[198:205], v[72:75], v189, v189 op_sel_hi:[0,0,0]
	v_mfma_scale_f32_16x16x128_f8f6f4 v[68:71], v[0:7], v[206:213], v[68:71], v189, v189 op_sel_hi:[0,0,0]
	v_mfma_scale_f32_16x16x128_f8f6f4 v[64:67], v[8:15], v[206:213], v[64:67], v189, v189 op_sel_hi:[0,0,0]
	s_setprio 0
	s_barrier
	s_add_i32 s24, s90, s80
	v_lshl_add_u64 v[174:175], s[66:67], 0, v[162:163]
	s_mov_b32 m0, s24
	ds_read_b128 v[190:193], v188 offset:16384
	ds_read_b128 v[194:197], v188 offset:17408
	ds_read_b128 v[198:201], v188 offset:18432
	ds_read_b128 v[202:205], v188 offset:19456
	ds_read_b128 v[206:209], v188 offset:20480
	ds_read_b128 v[210:213], v188 offset:21504
	ds_read_b128 v[214:217], v188 offset:22528
	ds_read_b128 v[218:221], v188 offset:23552
	global_load_lds_dwordx4 v[174:175], off
	s_add_i32 m0, s24, 0x2000
	s_add_u32 s24, s66, 0x40000
	v_lshl_add_u64 v[176:177], s[66:67], 0, v[166:167]
	s_addc_u32 s25, s67, 0
	s_add_i32 s26, s91, s80
	global_load_lds_dwordx4 v[176:177], off
	v_lshl_add_u64 v[178:179], s[24:25], 0, v[162:163]
	s_mov_b32 m0, s26
	v_lshl_add_u64 v[180:181], s[68:69], 0, v[164:165]
	global_load_lds_dwordx4 v[178:179], off
	v_lshl_add_u64 v[178:179], s[24:25], 0, v[166:167]
	s_add_i32 m0, s26, 0x2000
	s_nop 0
	global_load_lds_dwordx4 v[178:179], off
	v_lshl_add_u64 v[178:179], s[68:69], 0, v[160:161]
	s_mov_b32 m0, s81
	s_nop 0
	global_load_lds_dwordx4 v[178:179], off
	s_mov_b32 m0, s82
	s_nop 0
	global_load_lds_dwordx4 v[180:181], off
	s_waitcnt vmcnt(8)
	s_waitcnt lgkmcnt(0)
	s_barrier
	s_setprio 1
	s_waitcnt lgkmcnt(0)
	v_mfma_scale_f32_16x16x128_f8f6f4 v[124:127], v[16:23], v[190:197], v[124:127], v189, v189 op_sel_hi:[0,0,0]
	v_mfma_scale_f32_16x16x128_f8f6f4 v[120:123], v[24:31], v[190:197], v[120:123], v189, v189 op_sel_hi:[0,0,0]
	v_mfma_scale_f32_16x16x128_f8f6f4 v[116:119], v[16:23], v[198:205], v[116:119], v189, v189 op_sel_hi:[0,0,0]
	v_mfma_scale_f32_16x16x128_f8f6f4 v[112:115], v[24:31], v[198:205], v[112:115], v189, v189 op_sel_hi:[0,0,0]
	v_mfma_scale_f32_16x16x128_f8f6f4 v[108:111], v[16:23], v[206:213], v[108:111], v189, v189 op_sel_hi:[0,0,0]
	v_mfma_scale_f32_16x16x128_f8f6f4 v[104:107], v[24:31], v[206:213], v[104:107], v189, v189 op_sel_hi:[0,0,0]
	v_mfma_scale_f32_16x16x128_f8f6f4 v[100:103], v[16:23], v[214:221], v[100:103], v189, v189 op_sel_hi:[0,0,0]
	v_mfma_scale_f32_16x16x128_f8f6f4 v[96:99], v[24:31], v[214:221], v[96:99], v189, v189 op_sel_hi:[0,0,0]
	s_setprio 0
	s_setprio 1
	v_mfma_scale_f32_16x16x128_f8f6f4 v[60:63], v[0:7], v[190:197], v[60:63], v189, v189 op_sel_hi:[0,0,0]
	v_mfma_scale_f32_16x16x128_f8f6f4 v[56:59], v[8:15], v[190:197], v[56:59], v189, v189 op_sel_hi:[0,0,0]
	v_mfma_scale_f32_16x16x128_f8f6f4 v[52:55], v[0:7], v[198:205], v[52:55], v189, v189 op_sel_hi:[0,0,0]
	v_mfma_scale_f32_16x16x128_f8f6f4 v[48:51], v[8:15], v[198:205], v[48:51], v189, v189 op_sel_hi:[0,0,0]
	v_mfma_scale_f32_16x16x128_f8f6f4 v[44:47], v[0:7], v[206:213], v[44:47], v189, v189 op_sel_hi:[0,0,0]
	v_mfma_scale_f32_16x16x128_f8f6f4 v[40:43], v[8:15], v[206:213], v[40:43], v189, v189 op_sel_hi:[0,0,0]
	v_mfma_scale_f32_16x16x128_f8f6f4 v[36:39], v[0:7], v[214:221], v[36:39], v189, v189 op_sel_hi:[0,0,0]
	v_mfma_scale_f32_16x16x128_f8f6f4 v[32:35], v[8:15], v[214:221], v[32:35], v189, v189 op_sel_hi:[0,0,0]
	s_setprio 0
	s_barrier
	s_add_i32 s26, 0, 0x18000
	s_add_i32 s27, 0, 0x1c000
	v_add_u32_e32 v12, s26, v184
	v_add_u32_e32 v28, s27, v184
	ds_read_b128 v[0:3], v12
	ds_read_b128 v[4:7], v12 offset:1024
	ds_read_b128 v[8:11], v12 offset:2048
	ds_read_b128 v[12:15], v12 offset:3072
	ds_read_b128 v[16:19], v28
	ds_read_b128 v[20:23], v28 offset:1024
	ds_read_b128 v[24:27], v28 offset:2048
	ds_read_b128 v[28:31], v28 offset:3072
	s_add_u32 s24, s68, 0x40000
	s_addc_u32 s25, s69, 0
	s_mov_b32 m0, s83
	v_lshl_add_u64 v[222:223], s[24:25], 0, v[160:161]
	ds_read_b128 v[190:193], v188 offset:32768
	ds_read_b128 v[194:197], v188 offset:33792
	ds_read_b128 v[198:201], v188 offset:34816
	ds_read_b128 v[202:205], v188 offset:35840
	ds_read_b128 v[206:209], v188 offset:36864
	ds_read_b128 v[210:213], v188 offset:37888
	ds_read_b128 v[214:217], v188 offset:38912
	ds_read_b128 v[218:221], v188 offset:39936
	global_load_lds_dwordx4 v[222:223], off
	v_lshl_add_u64 v[222:223], s[24:25], 0, v[164:165]
	s_mov_b32 m0, s84
	s_nop 0
	global_load_lds_dwordx4 v[222:223], off
	s_waitcnt vmcnt(8)
	s_waitcnt lgkmcnt(0)
	s_barrier
	s_setprio 1
	s_waitcnt lgkmcnt(0)
	v_mfma_scale_f32_16x16x128_f8f6f4 v[156:159], v[0:7], v[190:197], v[156:159], v189, v189 op_sel_hi:[0,0,0]
	v_mfma_scale_f32_16x16x128_f8f6f4 v[152:155], v[8:15], v[190:197], v[152:155], v189, v189 op_sel_hi:[0,0,0]
	v_mfma_scale_f32_16x16x128_f8f6f4 v[148:151], v[0:7], v[198:205], v[148:151], v189, v189 op_sel_hi:[0,0,0]
	v_mfma_scale_f32_16x16x128_f8f6f4 v[144:147], v[8:15], v[198:205], v[144:147], v189, v189 op_sel_hi:[0,0,0]
	v_mfma_scale_f32_16x16x128_f8f6f4 v[140:143], v[0:7], v[206:213], v[140:143], v189, v189 op_sel_hi:[0,0,0]
	v_mfma_scale_f32_16x16x128_f8f6f4 v[136:139], v[8:15], v[206:213], v[136:139], v189, v189 op_sel_hi:[0,0,0]
	v_mfma_scale_f32_16x16x128_f8f6f4 v[132:135], v[0:7], v[214:221], v[132:135], v189, v189 op_sel_hi:[0,0,0]
	v_mfma_scale_f32_16x16x128_f8f6f4 v[128:131], v[8:15], v[214:221], v[128:131], v189, v189 op_sel_hi:[0,0,0]
	s_setprio 0
	s_setprio 1
	v_mfma_scale_f32_16x16x128_f8f6f4 v[92:95], v[16:23], v[190:197], v[92:95], v189, v189 op_sel_hi:[0,0,0]
	v_mfma_scale_f32_16x16x128_f8f6f4 v[88:91], v[24:31], v[190:197], v[88:91], v189, v189 op_sel_hi:[0,0,0]
	v_mfma_scale_f32_16x16x128_f8f6f4 v[84:87], v[16:23], v[198:205], v[84:87], v189, v189 op_sel_hi:[0,0,0]
	v_mfma_scale_f32_16x16x128_f8f6f4 v[80:83], v[24:31], v[198:205], v[80:83], v189, v189 op_sel_hi:[0,0,0]
	v_mfma_scale_f32_16x16x128_f8f6f4 v[76:79], v[16:23], v[206:213], v[76:79], v189, v189 op_sel_hi:[0,0,0]
	v_mfma_scale_f32_16x16x128_f8f6f4 v[72:75], v[24:31], v[206:213], v[72:75], v189, v189 op_sel_hi:[0,0,0]
	v_mfma_scale_f32_16x16x128_f8f6f4 v[68:71], v[16:23], v[214:221], v[68:71], v189, v189 op_sel_hi:[0,0,0]
	v_mfma_scale_f32_16x16x128_f8f6f4 v[64:67], v[24:31], v[214:221], v[64:67], v189, v189 op_sel_hi:[0,0,0]
	s_setprio 0
	s_barrier
	s_add_i32 s24, s26, s80
	v_lshl_add_u64 v[174:175], v[174:175], 0, s[12:13]
	s_mov_b32 m0, s24
	ds_read_b128 v[190:193], v188 offset:49152
	ds_read_b128 v[194:197], v188 offset:50176
	ds_read_b128 v[198:201], v188 offset:51200
	ds_read_b128 v[202:205], v188 offset:52224
	ds_read_b128 v[206:209], v188 offset:53248
	ds_read_b128 v[210:213], v188 offset:54272
	ds_read_b128 v[214:217], v188 offset:55296
	ds_read_b128 v[218:221], v188 offset:56320
	global_load_lds_dwordx4 v[174:175], off
	s_add_i32 m0, s24, 0x2000
	s_add_u32 s24, s66, 0x40080
	v_lshl_add_u64 v[174:175], v[176:177], 0, s[12:13]
	s_addc_u32 s25, s67, 0
	s_add_i32 s26, s27, s80
	global_load_lds_dwordx4 v[174:175], off
	v_lshl_add_u64 v[174:175], s[24:25], 0, v[162:163]
	s_mov_b32 m0, s26
	s_nop 0
	global_load_lds_dwordx4 v[174:175], off
	v_lshl_add_u64 v[174:175], s[24:25], 0, v[166:167]
	s_add_i32 m0, s26, 0x2000
	s_nop 0
	global_load_lds_dwordx4 v[174:175], off
	v_lshl_add_u64 v[174:175], v[178:179], 0, s[12:13]
	s_mov_b32 m0, s86
	s_nop 0
	global_load_lds_dwordx4 v[174:175], off
	v_lshl_add_u64 v[174:175], v[180:181], 0, s[12:13]
	s_mov_b32 m0, s87
	s_nop 0
	global_load_lds_dwordx4 v[174:175], off
	s_waitcnt vmcnt(8)
	s_waitcnt lgkmcnt(0)
	s_barrier
	s_setprio 1
	s_waitcnt lgkmcnt(0)
	v_mfma_scale_f32_16x16x128_f8f6f4 v[124:127], v[0:7], v[190:197], v[124:127], v189, v189 op_sel_hi:[0,0,0]
	v_mfma_scale_f32_16x16x128_f8f6f4 v[120:123], v[8:15], v[190:197], v[120:123], v189, v189 op_sel_hi:[0,0,0]
	v_mfma_scale_f32_16x16x128_f8f6f4 v[116:119], v[0:7], v[198:205], v[116:119], v189, v189 op_sel_hi:[0,0,0]
	v_mfma_scale_f32_16x16x128_f8f6f4 v[112:115], v[8:15], v[198:205], v[112:115], v189, v189 op_sel_hi:[0,0,0]
	v_mfma_scale_f32_16x16x128_f8f6f4 v[108:111], v[0:7], v[206:213], v[108:111], v189, v189 op_sel_hi:[0,0,0]
	v_mfma_scale_f32_16x16x128_f8f6f4 v[104:107], v[8:15], v[206:213], v[104:107], v189, v189 op_sel_hi:[0,0,0]
	v_mfma_scale_f32_16x16x128_f8f6f4 v[100:103], v[0:7], v[214:221], v[100:103], v189, v189 op_sel_hi:[0,0,0]
	v_mfma_scale_f32_16x16x128_f8f6f4 v[96:99], v[8:15], v[214:221], v[96:99], v189, v189 op_sel_hi:[0,0,0]
	s_setprio 0
	s_setprio 1
	v_mfma_scale_f32_16x16x128_f8f6f4 v[60:63], v[16:23], v[190:197], v[60:63], v189, v189 op_sel_hi:[0,0,0]
	v_mfma_scale_f32_16x16x128_f8f6f4 v[56:59], v[24:31], v[190:197], v[56:59], v189, v189 op_sel_hi:[0,0,0]
	v_mfma_scale_f32_16x16x128_f8f6f4 v[52:55], v[16:23], v[198:205], v[52:55], v189, v189 op_sel_hi:[0,0,0]
	v_mfma_scale_f32_16x16x128_f8f6f4 v[48:51], v[24:31], v[198:205], v[48:51], v189, v189 op_sel_hi:[0,0,0]
	v_mfma_scale_f32_16x16x128_f8f6f4 v[44:47], v[16:23], v[206:213], v[44:47], v189, v189 op_sel_hi:[0,0,0]
	v_mfma_scale_f32_16x16x128_f8f6f4 v[40:43], v[24:31], v[206:213], v[40:43], v189, v189 op_sel_hi:[0,0,0]
	v_mfma_scale_f32_16x16x128_f8f6f4 v[36:39], v[16:23], v[214:221], v[36:39], v189, v189 op_sel_hi:[0,0,0]
	v_mfma_scale_f32_16x16x128_f8f6f4 v[32:35], v[24:31], v[214:221], v[32:35], v189, v189 op_sel_hi:[0,0,0]
	s_setprio 0
	s_barrier
	s_add_i32 s71, s71, 2
	s_add_u32 s62, s62, 0x100
	s_addc_u32 s63, s63, 0
	s_add_u32 s65, s65, 0x100
	s_addc_u32 s70, s70, 0
	s_cmp_gt_u32 s71, 13
	s_cbranch_scc0 .LBB0_349
	s_and_b64 vcc, exec, s[18:19]
	s_cbranch_vccz .LBB0_352
	s_barrier

.LBB0_738:
	ds_read_b128 v[16:19], v189
	ds_read_b128 v[20:23], v189 offset:1024
	ds_read_b128 v[24:27], v189 offset:2048
	ds_read_b128 v[28:31], v189 offset:3072
	ds_read_b128 v[0:3], v190
	ds_read_b128 v[4:7], v190 offset:1024
	ds_read_b128 v[8:11], v190 offset:2048
	ds_read_b128 v[12:15], v190 offset:3072
	s_add_u32 s28, s62, 0xfffc0080
	s_addc_u32 s29, s63, -1
	s_cmp_eq_u32 s87, 12
	s_cselect_b32 s67, s47, s29
	s_cselect_b32 s66, s83, s28
	s_cselect_b32 s65, s45, s86
	s_cselect_b32 s64, s84, s85
	v_lshl_add_u64 v[218:219], s[62:63], 0, v[170:171]
	s_add_i32 m0, s61, 0xc000
	ds_read_b128 v[178:181], v191
	ds_read_b128 v[182:185], v191 offset:1024
	ds_read_b128 v[194:197], v191 offset:2048
	ds_read_b128 v[198:201], v191 offset:3072
	ds_read_b128 v[202:205], v191 offset:4096
	ds_read_b128 v[206:209], v191 offset:5120
	ds_read_b128 v[210:213], v191 offset:6144
	ds_read_b128 v[214:217], v191 offset:7168
	global_load_lds_dwordx4 v[218:219], off
	v_lshl_add_u64 v[218:219], s[62:63], 0, v[172:173]
	s_add_i32 m0, s61, 0xe000
	s_nop 0
	global_load_lds_dwordx4 v[218:219], off
	s_waitcnt vmcnt(8)
	s_waitcnt lgkmcnt(0)
	s_barrier
	s_setprio 1
	s_waitcnt lgkmcnt(0)
	v_mfma_scale_f32_16x16x128_f8f6f4 v[156:159], v[16:23], v[178:185], v[156:159], v192, v192 op_sel_hi:[0,0,0]
	v_mfma_scale_f32_16x16x128_f8f6f4 v[152:155], v[24:31], v[178:185], v[152:155], v192, v192 op_sel_hi:[0,0,0]
	v_mfma_scale_f32_16x16x128_f8f6f4 v[148:151], v[16:23], v[194:201], v[148:151], v192, v192 op_sel_hi:[0,0,0]
	v_mfma_scale_f32_16x16x128_f8f6f4 v[144:147], v[24:31], v[194:201], v[144:147], v192, v192 op_sel_hi:[0,0,0]
	v_mfma_scale_f32_16x16x128_f8f6f4 v[140:143], v[16:23], v[202:209], v[140:143], v192, v192 op_sel_hi:[0,0,0]
	v_mfma_scale_f32_16x16x128_f8f6f4 v[136:139], v[24:31], v[202:209], v[136:139], v192, v192 op_sel_hi:[0,0,0]
	v_mfma_scale_f32_16x16x128_f8f6f4 v[132:135], v[16:23], v[210:217], v[132:135], v192, v192 op_sel_hi:[0,0,0]
	v_mfma_scale_f32_16x16x128_f8f6f4 v[128:131], v[24:31], v[210:217], v[128:131], v192, v192 op_sel_hi:[0,0,0]
	s_setprio 0
	s_setprio 1
	v_mfma_scale_f32_16x16x128_f8f6f4 v[100:103], v[0:7], v[178:185], v[100:103], v192, v192 op_sel_hi:[0,0,0]
	v_mfma_scale_f32_16x16x128_f8f6f4 v[96:99], v[8:15], v[178:185], v[96:99], v192, v192 op_sel_hi:[0,0,0]
	v_mfma_scale_f32_16x16x128_f8f6f4 v[84:87], v[0:7], v[194:201], v[84:87], v192, v192 op_sel_hi:[0,0,0]
	v_mfma_scale_f32_16x16x128_f8f6f4 v[80:83], v[8:15], v[194:201], v[80:83], v192, v192 op_sel_hi:[0,0,0]
	v_mfma_scale_f32_16x16x128_f8f6f4 v[76:79], v[0:7], v[202:209], v[76:79], v192, v192 op_sel_hi:[0,0,0]
	v_mfma_scale_f32_16x16x128_f8f6f4 v[72:75], v[8:15], v[202:209], v[72:75], v192, v192 op_sel_hi:[0,0,0]
	v_mfma_scale_f32_16x16x128_f8f6f4 v[68:71], v[0:7], v[210:217], v[68:71], v192, v192 op_sel_hi:[0,0,0]
	v_mfma_scale_f32_16x16x128_f8f6f4 v[64:67], v[8:15], v[210:217], v[64:67], v192, v192 op_sel_hi:[0,0,0]
	s_setprio 0
	s_barrier
	s_add_i32 s28, s80, s23
	v_lshl_add_u64 v[178:179], s[64:65], 0, v[162:163]
	s_mov_b32 m0, s28
	ds_read_b128 v[194:197], v191 offset:16384
	ds_read_b128 v[198:201], v191 offset:17408
	ds_read_b128 v[202:205], v191 offset:18432
	ds_read_b128 v[206:209], v191 offset:19456
	ds_read_b128 v[210:213], v191 offset:20480
	ds_read_b128 v[214:217], v191 offset:21504
	ds_read_b128 v[218:221], v191 offset:22528
	ds_read_b128 v[222:225], v191 offset:23552
	global_load_lds_dwordx4 v[178:179], off
	s_add_i32 m0, s28, 0x2000
	s_add_u32 s28, s64, 0x40000
	v_lshl_add_u64 v[180:181], s[64:65], 0, v[166:167]
	s_addc_u32 s29, s65, 0
	s_add_i32 s30, s81, s23
	global_load_lds_dwordx4 v[180:181], off
	v_lshl_add_u64 v[182:183], s[28:29], 0, v[162:163]
	s_mov_b32 m0, s30
	v_lshl_add_u64 v[184:185], s[66:67], 0, v[164:165]
	global_load_lds_dwordx4 v[182:183], off
	v_lshl_add_u64 v[182:183], s[28:29], 0, v[166:167]
	s_add_i32 m0, s30, 0x2000
	s_nop 0
	global_load_lds_dwordx4 v[182:183], off
	v_lshl_add_u64 v[182:183], s[66:67], 0, v[160:161]
	s_mov_b32 m0, s61
	s_nop 0
	global_load_lds_dwordx4 v[182:183], off
	s_mov_b32 m0, s72
	s_nop 0
	global_load_lds_dwordx4 v[184:185], off
	s_waitcnt vmcnt(8)
	s_waitcnt lgkmcnt(0)
	s_barrier
	s_setprio 1
	s_waitcnt lgkmcnt(0)
	v_mfma_scale_f32_16x16x128_f8f6f4 v[124:127], v[16:23], v[194:201], v[124:127], v192, v192 op_sel_hi:[0,0,0]
	v_mfma_scale_f32_16x16x128_f8f6f4 v[120:123], v[24:31], v[194:201], v[120:123], v192, v192 op_sel_hi:[0,0,0]
	v_mfma_scale_f32_16x16x128_f8f6f4 v[116:119], v[16:23], v[202:209], v[116:119], v192, v192 op_sel_hi:[0,0,0]
	v_mfma_scale_f32_16x16x128_f8f6f4 v[112:115], v[24:31], v[202:209], v[112:115], v192, v192 op_sel_hi:[0,0,0]
	v_mfma_scale_f32_16x16x128_f8f6f4 v[108:111], v[16:23], v[210:217], v[108:111], v192, v192 op_sel_hi:[0,0,0]
	v_mfma_scale_f32_16x16x128_f8f6f4 v[104:107], v[24:31], v[210:217], v[104:107], v192, v192 op_sel_hi:[0,0,0]
	v_mfma_scale_f32_16x16x128_f8f6f4 v[92:95], v[16:23], v[218:225], v[92:95], v192, v192 op_sel_hi:[0,0,0]
	v_mfma_scale_f32_16x16x128_f8f6f4 v[88:91], v[24:31], v[218:225], v[88:91], v192, v192 op_sel_hi:[0,0,0]
	s_setprio 0
	s_setprio 1
	v_mfma_scale_f32_16x16x128_f8f6f4 v[60:63], v[0:7], v[194:201], v[60:63], v192, v192 op_sel_hi:[0,0,0]
	v_mfma_scale_f32_16x16x128_f8f6f4 v[56:59], v[8:15], v[194:201], v[56:59], v192, v192 op_sel_hi:[0,0,0]
	v_mfma_scale_f32_16x16x128_f8f6f4 v[52:55], v[0:7], v[202:209], v[52:55], v192, v192 op_sel_hi:[0,0,0]
	v_mfma_scale_f32_16x16x128_f8f6f4 v[48:51], v[8:15], v[202:209], v[48:51], v192, v192 op_sel_hi:[0,0,0]
	v_mfma_scale_f32_16x16x128_f8f6f4 v[44:47], v[0:7], v[210:217], v[44:47], v192, v192 op_sel_hi:[0,0,0]
	v_mfma_scale_f32_16x16x128_f8f6f4 v[40:43], v[8:15], v[210:217], v[40:43], v192, v192 op_sel_hi:[0,0,0]
	v_mfma_scale_f32_16x16x128_f8f6f4 v[36:39], v[0:7], v[218:225], v[36:39], v192, v192 op_sel_hi:[0,0,0]
	v_mfma_scale_f32_16x16x128_f8f6f4 v[32:35], v[8:15], v[218:225], v[32:35], v192, v192 op_sel_hi:[0,0,0]
	s_setprio 0
	s_barrier
	s_add_i32 s30, 0, 0x18000
	s_add_i32 s31, 0, 0x1c000
	v_add_u32_e32 v12, s30, v187
	v_add_u32_e32 v28, s31, v187
	ds_read_b128 v[0:3], v12
	ds_read_b128 v[4:7], v12 offset:1024
	ds_read_b128 v[8:11], v12 offset:2048
	ds_read_b128 v[12:15], v12 offset:3072
	ds_read_b128 v[16:19], v28
	ds_read_b128 v[20:23], v28 offset:1024
	ds_read_b128 v[24:27], v28 offset:2048
	ds_read_b128 v[28:31], v28 offset:3072
	s_add_u32 s28, s66, 0x40000
	s_addc_u32 s29, s67, 0
	s_mov_b32 m0, s73
	v_lshl_add_u64 v[226:227], s[28:29], 0, v[160:161]
	ds_read_b128 v[194:197], v191 offset:32768
	ds_read_b128 v[198:201], v191 offset:33792
	ds_read_b128 v[202:205], v191 offset:34816
	ds_read_b128 v[206:209], v191 offset:35840
	ds_read_b128 v[210:213], v191 offset:36864
	ds_read_b128 v[214:217], v191 offset:37888
	ds_read_b128 v[218:221], v191 offset:38912
	ds_read_b128 v[222:225], v191 offset:39936
	global_load_lds_dwordx4 v[226:227], off
	v_lshl_add_u64 v[226:227], s[28:29], 0, v[164:165]
	s_mov_b32 m0, s74
	s_nop 0
	global_load_lds_dwordx4 v[226:227], off
	s_waitcnt vmcnt(8)
	s_waitcnt lgkmcnt(0)
	s_barrier
	s_setprio 1
	s_waitcnt lgkmcnt(0)
	v_mfma_scale_f32_16x16x128_f8f6f4 v[156:159], v[0:7], v[194:201], v[156:159], v192, v192 op_sel_hi:[0,0,0]
	v_mfma_scale_f32_16x16x128_f8f6f4 v[152:155], v[8:15], v[194:201], v[152:155], v192, v192 op_sel_hi:[0,0,0]
	v_mfma_scale_f32_16x16x128_f8f6f4 v[148:151], v[0:7], v[202:209], v[148:151], v192, v192 op_sel_hi:[0,0,0]
	v_mfma_scale_f32_16x16x128_f8f6f4 v[144:147], v[8:15], v[202:209], v[144:147], v192, v192 op_sel_hi:[0,0,0]
	v_mfma_scale_f32_16x16x128_f8f6f4 v[140:143], v[0:7], v[210:217], v[140:143], v192, v192 op_sel_hi:[0,0,0]
	v_mfma_scale_f32_16x16x128_f8f6f4 v[136:139], v[8:15], v[210:217], v[136:139], v192, v192 op_sel_hi:[0,0,0]
	v_mfma_scale_f32_16x16x128_f8f6f4 v[132:135], v[0:7], v[218:225], v[132:135], v192, v192 op_sel_hi:[0,0,0]
	v_mfma_scale_f32_16x16x128_f8f6f4 v[128:131], v[8:15], v[218:225], v[128:131], v192, v192 op_sel_hi:[0,0,0]
	s_setprio 0
	s_setprio 1
	v_mfma_scale_f32_16x16x128_f8f6f4 v[100:103], v[16:23], v[194:201], v[100:103], v192, v192 op_sel_hi:[0,0,0]
	v_mfma_scale_f32_16x16x128_f8f6f4 v[96:99], v[24:31], v[194:201], v[96:99], v192, v192 op_sel_hi:[0,0,0]
	v_mfma_scale_f32_16x16x128_f8f6f4 v[84:87], v[16:23], v[202:209], v[84:87], v192, v192 op_sel_hi:[0,0,0]
	v_mfma_scale_f32_16x16x128_f8f6f4 v[80:83], v[24:31], v[202:209], v[80:83], v192, v192 op_sel_hi:[0,0,0]
	v_mfma_scale_f32_16x16x128_f8f6f4 v[76:79], v[16:23], v[210:217], v[76:79], v192, v192 op_sel_hi:[0,0,0]
	v_mfma_scale_f32_16x16x128_f8f6f4 v[72:75], v[24:31], v[210:217], v[72:75], v192, v192 op_sel_hi:[0,0,0]
	v_mfma_scale_f32_16x16x128_f8f6f4 v[68:71], v[16:23], v[218:225], v[68:71], v192, v192 op_sel_hi:[0,0,0]
	v_mfma_scale_f32_16x16x128_f8f6f4 v[64:67], v[24:31], v[218:225], v[64:67], v192, v192 op_sel_hi:[0,0,0]
	s_setprio 0
	s_barrier
	s_add_i32 s28, s30, s23
	v_lshl_add_u64 v[178:179], v[178:179], 0, s[12:13]
	s_mov_b32 m0, s28
	ds_read_b128 v[194:197], v191 offset:49152
	ds_read_b128 v[198:201], v191 offset:50176
	ds_read_b128 v[202:205], v191 offset:51200
	ds_read_b128 v[206:209], v191 offset:52224
	ds_read_b128 v[210:213], v191 offset:53248
	ds_read_b128 v[214:217], v191 offset:54272
	ds_read_b128 v[218:221], v191 offset:55296
	ds_read_b128 v[222:225], v191 offset:56320
	global_load_lds_dwordx4 v[178:179], off
	s_add_i32 m0, s28, 0x2000
	s_add_u32 s28, s64, 0x40080
	v_lshl_add_u64 v[178:179], v[180:181], 0, s[12:13]
	s_addc_u32 s29, s65, 0
	s_add_i32 s30, s31, s23
	global_load_lds_dwordx4 v[178:179], off
	v_lshl_add_u64 v[178:179], s[28:29], 0, v[162:163]
	s_mov_b32 m0, s30
	s_nop 0
	global_load_lds_dwordx4 v[178:179], off
	v_lshl_add_u64 v[178:179], s[28:29], 0, v[166:167]
	s_add_i32 m0, s30, 0x2000
	s_nop 0
	global_load_lds_dwordx4 v[178:179], off
	v_lshl_add_u64 v[178:179], v[182:183], 0, s[12:13]
	s_mov_b32 m0, s76
	s_nop 0
	global_load_lds_dwordx4 v[178:179], off
	v_lshl_add_u64 v[178:179], v[184:185], 0, s[12:13]
	s_mov_b32 m0, s77
	s_nop 0
	global_load_lds_dwordx4 v[178:179], off
	s_waitcnt vmcnt(8)
	s_waitcnt lgkmcnt(0)
	s_barrier
	s_setprio 1
	s_waitcnt lgkmcnt(0)
	v_mfma_scale_f32_16x16x128_f8f6f4 v[124:127], v[0:7], v[194:201], v[124:127], v192, v192 op_sel_hi:[0,0,0]
	v_mfma_scale_f32_16x16x128_f8f6f4 v[120:123], v[8:15], v[194:201], v[120:123], v192, v192 op_sel_hi:[0,0,0]
	v_mfma_scale_f32_16x16x128_f8f6f4 v[116:119], v[0:7], v[202:209], v[116:119], v192, v192 op_sel_hi:[0,0,0]
	v_mfma_scale_f32_16x16x128_f8f6f4 v[112:115], v[8:15], v[202:209], v[112:115], v192, v192 op_sel_hi:[0,0,0]
	v_mfma_scale_f32_16x16x128_f8f6f4 v[108:111], v[0:7], v[210:217], v[108:111], v192, v192 op_sel_hi:[0,0,0]
	v_mfma_scale_f32_16x16x128_f8f6f4 v[104:107], v[8:15], v[210:217], v[104:107], v192, v192 op_sel_hi:[0,0,0]
	v_mfma_scale_f32_16x16x128_f8f6f4 v[92:95], v[0:7], v[218:225], v[92:95], v192, v192 op_sel_hi:[0,0,0]
	v_mfma_scale_f32_16x16x128_f8f6f4 v[88:91], v[8:15], v[218:225], v[88:91], v192, v192 op_sel_hi:[0,0,0]
	s_setprio 0
	s_setprio 1
	v_mfma_scale_f32_16x16x128_f8f6f4 v[60:63], v[16:23], v[194:201], v[60:63], v192, v192 op_sel_hi:[0,0,0]
	v_mfma_scale_f32_16x16x128_f8f6f4 v[56:59], v[24:31], v[194:201], v[56:59], v192, v192 op_sel_hi:[0,0,0]
	v_mfma_scale_f32_16x16x128_f8f6f4 v[52:55], v[16:23], v[202:209], v[52:55], v192, v192 op_sel_hi:[0,0,0]
	v_mfma_scale_f32_16x16x128_f8f6f4 v[48:51], v[24:31], v[202:209], v[48:51], v192, v192 op_sel_hi:[0,0,0]
	v_mfma_scale_f32_16x16x128_f8f6f4 v[44:47], v[16:23], v[210:217], v[44:47], v192, v192 op_sel_hi:[0,0,0]
	v_mfma_scale_f32_16x16x128_f8f6f4 v[40:43], v[24:31], v[210:217], v[40:43], v192, v192 op_sel_hi:[0,0,0]
	v_mfma_scale_f32_16x16x128_f8f6f4 v[36:39], v[16:23], v[218:225], v[36:39], v192, v192 op_sel_hi:[0,0,0]
	v_mfma_scale_f32_16x16x128_f8f6f4 v[32:35], v[24:31], v[218:225], v[32:35], v192, v192 op_sel_hi:[0,0,0]
	s_setprio 0
	s_barrier
	s_add_i32 s87, s87, 2
	s_add_u32 s62, s62, 0x100
	s_addc_u32 s63, s63, 0
	s_add_u32 s85, s85, 0x100
	s_addc_u32 s86, s86, 0
	s_cmp_gt_u32 s87, 13
	s_cbranch_scc0 .LBB0_738
	s_and_b64 vcc, exec, s[14:15]
	s_cbranch_vccz .LBB0_741
	s_barrier

.LBB0_818:
	v_add_u32_e32 v0, s51, v193
	v_add_u32_e32 v12, s58, v193
	s_add_u32 s28, s12, s26
	ds_read_b128 v[16:19], v0
	ds_read_b128 v[20:23], v0 offset:1024
	ds_read_b128 v[24:27], v0 offset:2048
	ds_read_b128 v[28:31], v0 offset:3072
	ds_read_b128 v[0:3], v12
	ds_read_b128 v[4:7], v12 offset:1024
	ds_read_b128 v[8:11], v12 offset:2048
	ds_read_b128 v[12:15], v12 offset:3072
	s_addc_u32 s29, s13, s27
	s_add_u32 s28, s28, 0x100
	s_addc_u32 s29, s29, 0
	s_add_u32 s30, s23, s26
	s_addc_u32 s31, s59, s27
	s_cmpk_eq_i32 s26, 0x700
	s_cselect_b32 s41, s19, s29
	s_cselect_b32 s40, s60, s28
	s_cselect_b32 s39, s17, s31
	s_cselect_b32 s38, s61, s30
	v_lshl_add_u64 v[220:221], v[178:179], 0, s[26:27]
	s_add_i32 m0, s43, 0xc000
	ds_read_b128 v[182:185], v194
	ds_read_b128 v[186:189], v194 offset:1024
	ds_read_b128 v[196:199], v194 offset:2048
	ds_read_b128 v[200:203], v194 offset:3072
	ds_read_b128 v[204:207], v194 offset:4096
	ds_read_b128 v[208:211], v194 offset:5120
	ds_read_b128 v[212:215], v194 offset:6144
	ds_read_b128 v[216:219], v194 offset:7168
	global_load_lds_dwordx4 v[220:221], off
	v_lshl_add_u64 v[220:221], v[180:181], 0, s[26:27]
	s_add_i32 m0, s43, 0xe000
	s_nop 0
	global_load_lds_dwordx4 v[220:221], off
	s_waitcnt vmcnt(8)
	s_waitcnt lgkmcnt(0)
	s_barrier
	s_setprio 1
	s_waitcnt lgkmcnt(0)
	v_mfma_scale_f32_16x16x128_f8f6f4 v[156:159], v[16:23], v[182:189], v[156:159], v195, v195 op_sel_hi:[0,0,0]
	v_mfma_scale_f32_16x16x128_f8f6f4 v[152:155], v[24:31], v[182:189], v[152:155], v195, v195 op_sel_hi:[0,0,0]
	v_mfma_scale_f32_16x16x128_f8f6f4 v[148:151], v[16:23], v[196:203], v[148:151], v195, v195 op_sel_hi:[0,0,0]
	v_mfma_scale_f32_16x16x128_f8f6f4 v[144:147], v[24:31], v[196:203], v[144:147], v195, v195 op_sel_hi:[0,0,0]
	v_mfma_scale_f32_16x16x128_f8f6f4 v[140:143], v[16:23], v[204:211], v[140:143], v195, v195 op_sel_hi:[0,0,0]
	v_mfma_scale_f32_16x16x128_f8f6f4 v[136:139], v[24:31], v[204:211], v[136:139], v195, v195 op_sel_hi:[0,0,0]
	v_mfma_scale_f32_16x16x128_f8f6f4 v[132:135], v[16:23], v[212:219], v[132:135], v195, v195 op_sel_hi:[0,0,0]
	v_mfma_scale_f32_16x16x128_f8f6f4 v[128:131], v[24:31], v[212:219], v[128:131], v195, v195 op_sel_hi:[0,0,0]
	s_setprio 0
	s_setprio 1
	v_mfma_scale_f32_16x16x128_f8f6f4 v[92:95], v[0:7], v[182:189], v[92:95], v195, v195 op_sel_hi:[0,0,0]
	v_mfma_scale_f32_16x16x128_f8f6f4 v[88:91], v[8:15], v[182:189], v[88:91], v195, v195 op_sel_hi:[0,0,0]
	v_mfma_scale_f32_16x16x128_f8f6f4 v[84:87], v[0:7], v[196:203], v[84:87], v195, v195 op_sel_hi:[0,0,0]
	v_mfma_scale_f32_16x16x128_f8f6f4 v[80:83], v[8:15], v[196:203], v[80:83], v195, v195 op_sel_hi:[0,0,0]
	v_mfma_scale_f32_16x16x128_f8f6f4 v[76:79], v[0:7], v[204:211], v[76:79], v195, v195 op_sel_hi:[0,0,0]
	v_mfma_scale_f32_16x16x128_f8f6f4 v[72:75], v[8:15], v[204:211], v[72:75], v195, v195 op_sel_hi:[0,0,0]
	v_mfma_scale_f32_16x16x128_f8f6f4 v[68:71], v[0:7], v[212:219], v[68:71], v195, v195 op_sel_hi:[0,0,0]
	v_mfma_scale_f32_16x16x128_f8f6f4 v[64:67], v[8:15], v[212:219], v[64:67], v195, v195 op_sel_hi:[0,0,0]
	s_setprio 0
	s_barrier
	s_add_i32 s28, s51, s42
	v_lshl_add_u64 v[182:183], s[38:39], 0, v[162:163]
	s_mov_b32 m0, s28
	ds_read_b128 v[196:199], v194 offset:16384
	ds_read_b128 v[200:203], v194 offset:17408
	ds_read_b128 v[204:207], v194 offset:18432
	ds_read_b128 v[208:211], v194 offset:19456
	ds_read_b128 v[212:215], v194 offset:20480
	ds_read_b128 v[216:219], v194 offset:21504
	ds_read_b128 v[220:223], v194 offset:22528
	ds_read_b128 v[224:227], v194 offset:23552
	global_load_lds_dwordx4 v[182:183], off
	s_add_i32 m0, s28, 0x2000
	s_add_u32 s28, s38, 0x40000
	v_lshl_add_u64 v[184:185], s[38:39], 0, v[166:167]
	s_addc_u32 s29, s39, 0
	s_add_i32 s30, s58, s42
	global_load_lds_dwordx4 v[184:185], off
	v_lshl_add_u64 v[186:187], s[28:29], 0, v[162:163]
	s_mov_b32 m0, s30
	v_lshl_add_u64 v[188:189], s[40:41], 0, v[164:165]
	global_load_lds_dwordx4 v[186:187], off
	v_lshl_add_u64 v[186:187], s[28:29], 0, v[166:167]
	s_add_i32 m0, s30, 0x2000
	s_nop 0
	global_load_lds_dwordx4 v[186:187], off
	v_lshl_add_u64 v[186:187], s[40:41], 0, v[160:161]
	s_mov_b32 m0, s43
	s_nop 0
	global_load_lds_dwordx4 v[186:187], off
	s_mov_b32 m0, s44
	s_nop 0
	global_load_lds_dwordx4 v[188:189], off
	s_waitcnt vmcnt(8)
	s_waitcnt lgkmcnt(0)
	s_barrier
	s_setprio 1
	s_waitcnt lgkmcnt(0)
	v_mfma_scale_f32_16x16x128_f8f6f4 v[124:127], v[16:23], v[196:203], v[124:127], v195, v195 op_sel_hi:[0,0,0]
	v_mfma_scale_f32_16x16x128_f8f6f4 v[120:123], v[24:31], v[196:203], v[120:123], v195, v195 op_sel_hi:[0,0,0]
	v_mfma_scale_f32_16x16x128_f8f6f4 v[116:119], v[16:23], v[204:211], v[116:119], v195, v195 op_sel_hi:[0,0,0]
	v_mfma_scale_f32_16x16x128_f8f6f4 v[112:115], v[24:31], v[204:211], v[112:115], v195, v195 op_sel_hi:[0,0,0]
	v_mfma_scale_f32_16x16x128_f8f6f4 v[108:111], v[16:23], v[212:219], v[108:111], v195, v195 op_sel_hi:[0,0,0]
	v_mfma_scale_f32_16x16x128_f8f6f4 v[104:107], v[24:31], v[212:219], v[104:107], v195, v195 op_sel_hi:[0,0,0]
	v_mfma_scale_f32_16x16x128_f8f6f4 v[100:103], v[16:23], v[220:227], v[100:103], v195, v195 op_sel_hi:[0,0,0]
	v_mfma_scale_f32_16x16x128_f8f6f4 v[96:99], v[24:31], v[220:227], v[96:99], v195, v195 op_sel_hi:[0,0,0]
	s_setprio 0
	s_setprio 1
	v_mfma_scale_f32_16x16x128_f8f6f4 v[60:63], v[0:7], v[196:203], v[60:63], v195, v195 op_sel_hi:[0,0,0]
	v_mfma_scale_f32_16x16x128_f8f6f4 v[56:59], v[8:15], v[196:203], v[56:59], v195, v195 op_sel_hi:[0,0,0]
	v_mfma_scale_f32_16x16x128_f8f6f4 v[52:55], v[0:7], v[204:211], v[52:55], v195, v195 op_sel_hi:[0,0,0]
	v_mfma_scale_f32_16x16x128_f8f6f4 v[48:51], v[8:15], v[204:211], v[48:51], v195, v195 op_sel_hi:[0,0,0]
	v_mfma_scale_f32_16x16x128_f8f6f4 v[44:47], v[0:7], v[212:219], v[44:47], v195, v195 op_sel_hi:[0,0,0]
	v_mfma_scale_f32_16x16x128_f8f6f4 v[40:43], v[8:15], v[212:219], v[40:43], v195, v195 op_sel_hi:[0,0,0]
	v_mfma_scale_f32_16x16x128_f8f6f4 v[36:39], v[0:7], v[220:227], v[36:39], v195, v195 op_sel_hi:[0,0,0]
	v_mfma_scale_f32_16x16x128_f8f6f4 v[32:35], v[8:15], v[220:227], v[32:35], v195, v195 op_sel_hi:[0,0,0]
	s_setprio 0
	s_barrier
	s_add_i32 s30, 0, 0x18000
	s_add_i32 s31, 0, 0x1c000
	v_add_u32_e32 v12, s30, v193
	v_add_u32_e32 v28, s31, v193
	ds_read_b128 v[0:3], v12
	ds_read_b128 v[4:7], v12 offset:1024
	ds_read_b128 v[8:11], v12 offset:2048
	ds_read_b128 v[12:15], v12 offset:3072
	ds_read_b128 v[16:19], v28
	ds_read_b128 v[20:23], v28 offset:1024
	ds_read_b128 v[24:27], v28 offset:2048
	ds_read_b128 v[28:31], v28 offset:3072
	s_add_u32 s28, s40, 0x40000
	s_addc_u32 s29, s41, 0
	s_mov_b32 m0, s45
	v_lshl_add_u64 v[228:229], s[28:29], 0, v[160:161]
	ds_read_b128 v[196:199], v194 offset:32768
	ds_read_b128 v[200:203], v194 offset:33792
	ds_read_b128 v[204:207], v194 offset:34816
	ds_read_b128 v[208:211], v194 offset:35840
	ds_read_b128 v[212:215], v194 offset:36864
	ds_read_b128 v[216:219], v194 offset:37888
	ds_read_b128 v[220:223], v194 offset:38912
	ds_read_b128 v[224:227], v194 offset:39936
	global_load_lds_dwordx4 v[228:229], off
	v_lshl_add_u64 v[228:229], s[28:29], 0, v[164:165]
	s_mov_b32 m0, s46
	s_nop 0
	global_load_lds_dwordx4 v[228:229], off
	s_waitcnt vmcnt(8)
	s_waitcnt lgkmcnt(0)
	s_barrier
	s_setprio 1
	s_waitcnt lgkmcnt(0)
	v_mfma_scale_f32_16x16x128_f8f6f4 v[156:159], v[0:7], v[196:203], v[156:159], v195, v195 op_sel_hi:[0,0,0]
	v_mfma_scale_f32_16x16x128_f8f6f4 v[152:155], v[8:15], v[196:203], v[152:155], v195, v195 op_sel_hi:[0,0,0]
	v_mfma_scale_f32_16x16x128_f8f6f4 v[148:151], v[0:7], v[204:211], v[148:151], v195, v195 op_sel_hi:[0,0,0]
	v_mfma_scale_f32_16x16x128_f8f6f4 v[144:147], v[8:15], v[204:211], v[144:147], v195, v195 op_sel_hi:[0,0,0]
	v_mfma_scale_f32_16x16x128_f8f6f4 v[140:143], v[0:7], v[212:219], v[140:143], v195, v195 op_sel_hi:[0,0,0]
	v_mfma_scale_f32_16x16x128_f8f6f4 v[136:139], v[8:15], v[212:219], v[136:139], v195, v195 op_sel_hi:[0,0,0]
	v_mfma_scale_f32_16x16x128_f8f6f4 v[132:135], v[0:7], v[220:227], v[132:135], v195, v195 op_sel_hi:[0,0,0]
	v_mfma_scale_f32_16x16x128_f8f6f4 v[128:131], v[8:15], v[220:227], v[128:131], v195, v195 op_sel_hi:[0,0,0]
	s_setprio 0
	s_setprio 1
	v_mfma_scale_f32_16x16x128_f8f6f4 v[92:95], v[16:23], v[196:203], v[92:95], v195, v195 op_sel_hi:[0,0,0]
	v_mfma_scale_f32_16x16x128_f8f6f4 v[88:91], v[24:31], v[196:203], v[88:91], v195, v195 op_sel_hi:[0,0,0]
	v_mfma_scale_f32_16x16x128_f8f6f4 v[84:87], v[16:23], v[204:211], v[84:87], v195, v195 op_sel_hi:[0,0,0]
	v_mfma_scale_f32_16x16x128_f8f6f4 v[80:83], v[24:31], v[204:211], v[80:83], v195, v195 op_sel_hi:[0,0,0]
	v_mfma_scale_f32_16x16x128_f8f6f4 v[76:79], v[16:23], v[212:219], v[76:79], v195, v195 op_sel_hi:[0,0,0]
	v_mfma_scale_f32_16x16x128_f8f6f4 v[72:75], v[24:31], v[212:219], v[72:75], v195, v195 op_sel_hi:[0,0,0]
	v_mfma_scale_f32_16x16x128_f8f6f4 v[68:71], v[16:23], v[220:227], v[68:71], v195, v195 op_sel_hi:[0,0,0]
	v_mfma_scale_f32_16x16x128_f8f6f4 v[64:67], v[24:31], v[220:227], v[64:67], v195, v195 op_sel_hi:[0,0,0]
	s_setprio 0
	s_barrier
	s_add_i32 s28, s30, s42
	v_lshl_add_u64 v[182:183], v[182:183], 0, s[14:15]
	s_mov_b32 m0, s28
	ds_read_b128 v[196:199], v194 offset:49152
	ds_read_b128 v[200:203], v194 offset:50176
	ds_read_b128 v[204:207], v194 offset:51200
	ds_read_b128 v[208:211], v194 offset:52224
	ds_read_b128 v[212:215], v194 offset:53248
	ds_read_b128 v[216:219], v194 offset:54272
	ds_read_b128 v[220:223], v194 offset:55296
	ds_read_b128 v[224:227], v194 offset:56320
	global_load_lds_dwordx4 v[182:183], off
	s_add_i32 m0, s28, 0x2000
	s_add_u32 s28, s38, 0x40080
	v_lshl_add_u64 v[182:183], v[184:185], 0, s[14:15]
	s_addc_u32 s29, s39, 0
	s_add_i32 s30, s31, s42
	global_load_lds_dwordx4 v[182:183], off
	v_lshl_add_u64 v[182:183], s[28:29], 0, v[162:163]
	s_mov_b32 m0, s30
	s_nop 0
	global_load_lds_dwordx4 v[182:183], off
	v_lshl_add_u64 v[182:183], s[28:29], 0, v[166:167]
	s_add_i32 m0, s30, 0x2000
	s_nop 0
	global_load_lds_dwordx4 v[182:183], off
	v_lshl_add_u64 v[182:183], v[186:187], 0, s[14:15]
	s_mov_b32 m0, s49
	s_nop 0
	global_load_lds_dwordx4 v[182:183], off
	v_lshl_add_u64 v[182:183], v[188:189], 0, s[14:15]
	s_mov_b32 m0, s50
	s_nop 0
	global_load_lds_dwordx4 v[182:183], off
	s_waitcnt vmcnt(8)
	s_waitcnt lgkmcnt(0)
	s_barrier
	s_setprio 1
	s_waitcnt lgkmcnt(0)
	v_mfma_scale_f32_16x16x128_f8f6f4 v[124:127], v[0:7], v[196:203], v[124:127], v195, v195 op_sel_hi:[0,0,0]
	v_mfma_scale_f32_16x16x128_f8f6f4 v[120:123], v[8:15], v[196:203], v[120:123], v195, v195 op_sel_hi:[0,0,0]
	v_mfma_scale_f32_16x16x128_f8f6f4 v[116:119], v[0:7], v[204:211], v[116:119], v195, v195 op_sel_hi:[0,0,0]
	v_mfma_scale_f32_16x16x128_f8f6f4 v[112:115], v[8:15], v[204:211], v[112:115], v195, v195 op_sel_hi:[0,0,0]
	v_mfma_scale_f32_16x16x128_f8f6f4 v[108:111], v[0:7], v[212:219], v[108:111], v195, v195 op_sel_hi:[0,0,0]
	v_mfma_scale_f32_16x16x128_f8f6f4 v[104:107], v[8:15], v[212:219], v[104:107], v195, v195 op_sel_hi:[0,0,0]
	v_mfma_scale_f32_16x16x128_f8f6f4 v[100:103], v[0:7], v[220:227], v[100:103], v195, v195 op_sel_hi:[0,0,0]
	v_mfma_scale_f32_16x16x128_f8f6f4 v[96:99], v[8:15], v[220:227], v[96:99], v195, v195 op_sel_hi:[0,0,0]
	s_setprio 0
	s_setprio 1
	v_mfma_scale_f32_16x16x128_f8f6f4 v[60:63], v[16:23], v[196:203], v[60:63], v195, v195 op_sel_hi:[0,0,0]
	v_mfma_scale_f32_16x16x128_f8f6f4 v[56:59], v[24:31], v[196:203], v[56:59], v195, v195 op_sel_hi:[0,0,0]
	v_mfma_scale_f32_16x16x128_f8f6f4 v[52:55], v[16:23], v[204:211], v[52:55], v195, v195 op_sel_hi:[0,0,0]
	v_mfma_scale_f32_16x16x128_f8f6f4 v[48:51], v[24:31], v[204:211], v[48:51], v195, v195 op_sel_hi:[0,0,0]
	v_mfma_scale_f32_16x16x128_f8f6f4 v[44:47], v[16:23], v[212:219], v[44:47], v195, v195 op_sel_hi:[0,0,0]
	v_mfma_scale_f32_16x16x128_f8f6f4 v[40:43], v[24:31], v[212:219], v[40:43], v195, v195 op_sel_hi:[0,0,0]
	v_mfma_scale_f32_16x16x128_f8f6f4 v[36:39], v[16:23], v[220:227], v[36:39], v195, v195 op_sel_hi:[0,0,0]
	v_mfma_scale_f32_16x16x128_f8f6f4 v[32:35], v[24:31], v[220:227], v[32:35], v195, v195 op_sel_hi:[0,0,0]
	s_setprio 0
	s_barrier
	s_add_i32 s62, s62, 2
	s_add_u32 s26, s26, 0x100
	s_addc_u32 s27, s27, 0
	s_cmp_gt_u32 s62, 13
	s_cbranch_scc0 .LBB0_818
	s_add_u32 s26, s23, 0xffffff00
	s_addc_u32 s27, s59, -1
	s_andn2_b64 vcc, exec, s[4:5]
	s_cbranch_vccnz .LBB0_809
	v_mov_b32_e32 v32, 0
	s_mov_b32 s6, s16
	s_mov_b32 s10, s18
	s_mov_b64 s[12:13], s[24:25]
	s_mov_b32 s48, s22
	v_mov_b32_e32 v33, v32
	v_mov_b32_e32 v34, v32
	v_mov_b32_e32 v35, v32
	v_mov_b32_e32 v36, v32
	v_mov_b32_e32 v37, v32
	v_mov_b32_e32 v38, v32
	v_mov_b32_e32 v39, v32
	v_mov_b32_e32 v40, v32
	v_mov_b32_e32 v41, v32
	v_mov_b32_e32 v42, v32
	v_mov_b32_e32 v43, v32
	v_mov_b32_e32 v44, v32
	v_mov_b32_e32 v45, v32
	v_mov_b32_e32 v46, v32
	v_mov_b32_e32 v47, v32
	v_mov_b32_e32 v48, v32
	v_mov_b32_e32 v49, v32
	v_mov_b32_e32 v50, v32
	v_mov_b32_e32 v51, v32
	v_mov_b32_e32 v52, v32
	v_mov_b32_e32 v53, v32
	v_mov_b32_e32 v54, v32
	v_mov_b32_e32 v55, v32
	v_mov_b32_e32 v56, v32
	v_mov_b32_e32 v57, v32
	v_mov_b32_e32 v58, v32
	v_mov_b32_e32 v59, v32
	v_mov_b32_e32 v60, v32
	v_mov_b32_e32 v61, v32
	v_mov_b32_e32 v62, v32
	v_mov_b32_e32 v63, v32
	v_mov_b32_e32 v96, v32
	v_mov_b32_e32 v97, v32
	v_mov_b32_e32 v98, v32
	v_mov_b32_e32 v99, v32
	v_mov_b32_e32 v100, v32
	v_mov_b32_e32 v101, v32
	v_mov_b32_e32 v102, v32
	v_mov_b32_e32 v103, v32
	v_mov_b32_e32 v104, v32
	v_mov_b32_e32 v105, v32
	v_mov_b32_e32 v106, v32
	v_mov_b32_e32 v107, v32
	v_mov_b32_e32 v108, v32
	v_mov_b32_e32 v109, v32
	v_mov_b32_e32 v110, v32
	v_mov_b32_e32 v111, v32
	v_mov_b32_e32 v112, v32
	v_mov_b32_e32 v113, v32
	v_mov_b32_e32 v114, v32
	v_mov_b32_e32 v115, v32
	v_mov_b32_e32 v116, v32
	v_mov_b32_e32 v117, v32
	v_mov_b32_e32 v118, v32
	v_mov_b32_e32 v119, v32
	v_mov_b32_e32 v120, v32
	v_mov_b32_e32 v121, v32
	v_mov_b32_e32 v122, v32
	v_mov_b32_e32 v123, v32
	v_mov_b32_e32 v124, v32
	v_mov_b32_e32 v125, v32
	v_mov_b32_e32 v126, v32
	v_mov_b32_e32 v127, v32
	v_mov_b32_e32 v64, v32
	v_mov_b32_e32 v65, v32
	v_mov_b32_e32 v66, v32
	v_mov_b32_e32 v67, v32
	v_mov_b32_e32 v68, v32
	v_mov_b32_e32 v69, v32
	v_mov_b32_e32 v70, v32
	v_mov_b32_e32 v71, v32
	v_mov_b32_e32 v72, v32
	v_mov_b32_e32 v73, v32
	v_mov_b32_e32 v74, v32
	v_mov_b32_e32 v75, v32
	v_mov_b32_e32 v76, v32
	v_mov_b32_e32 v77, v32
	v_mov_b32_e32 v78, v32
	v_mov_b32_e32 v79, v32
	v_mov_b32_e32 v80, v32
	v_mov_b32_e32 v81, v32
	v_mov_b32_e32 v82, v32
	v_mov_b32_e32 v83, v32
	v_mov_b32_e32 v84, v32
	v_mov_b32_e32 v85, v32
	v_mov_b32_e32 v86, v32
	v_mov_b32_e32 v87, v32
	v_mov_b32_e32 v88, v32
	v_mov_b32_e32 v89, v32
	v_mov_b32_e32 v90, v32
	v_mov_b32_e32 v91, v32
	v_mov_b32_e32 v92, v32
	v_mov_b32_e32 v93, v32
	v_mov_b32_e32 v94, v32
	v_mov_b32_e32 v95, v32
	v_mov_b32_e32 v128, v32
	v_mov_b32_e32 v129, v32
	v_mov_b32_e32 v130, v32
	v_mov_b32_e32 v131, v32
	v_mov_b32_e32 v132, v32
	v_mov_b32_e32 v133, v32
	v_mov_b32_e32 v134, v32
	v_mov_b32_e32 v135, v32
	v_mov_b32_e32 v136, v32
	v_mov_b32_e32 v137, v32
	v_mov_b32_e32 v138, v32
	v_mov_b32_e32 v139, v32
	v_mov_b32_e32 v140, v32
	v_mov_b32_e32 v141, v32
	v_mov_b32_e32 v142, v32
	v_mov_b32_e32 v143, v32
	v_mov_b32_e32 v144, v32
	v_mov_b32_e32 v145, v32
	v_mov_b32_e32 v146, v32
	v_mov_b32_e32 v147, v32
	v_mov_b32_e32 v148, v32
	v_mov_b32_e32 v149, v32
	v_mov_b32_e32 v150, v32
	v_mov_b32_e32 v151, v32
	v_mov_b32_e32 v152, v32
	v_mov_b32_e32 v153, v32
	v_mov_b32_e32 v154, v32
	v_mov_b32_e32 v155, v32
	v_mov_b32_e32 v156, v32
	v_mov_b32_e32 v157, v32
	v_mov_b32_e32 v158, v32
	v_mov_b32_e32 v159, v32
	s_andn2_b64 vcc, exec, s[0:1]
	s_cbranch_vccnz .LBB0_810
